# attention fast trip: first P.V MFMA of phase B issued ahead of the step's two LDS-DMA blocks
# baseline (speedup 1.0000x reference)
.Lfast3:
.Lf3_0_485:
	s_waitcnt lgkmcnt(9)
	v_mfma_f32_32x32x16_bf16 v[98:113], v[174:177], v[142:145], v[34:49]
	ds_read_b64_tr_b16 v[178:179], v203 offset:24576
	ds_read_b64_tr_b16 v[180:181], v203 offset:25088
	v_add_f32_e32 v82, v66, v67
	v_add_f32_e32 v82, v68, v82
	v_add_f32_e32 v82, v69, v82
	v_add_f32_e32 v82, v70, v82
	v_add_f32_e32 v82, v71, v82
	v_cvt_pk_bf16_f32 v138, v66, v67
	v_cvt_pk_bf16_f32 v139, v68, v69
	ds_read_b64_tr_b16 v[174:175], v203 offset:28672
	ds_read_b64_tr_b16 v[176:177], v203 offset:29184
	v_add_f32_e32 v66, v72, v82
	s_waitcnt lgkmcnt(10)
	v_mfma_f32_32x32x16_bf16 v[82:97], v[170:173], v[142:145], v[34:49]
	v_add_f32_e32 v66, v73, v66
	v_add_f32_e32 v66, v74, v66
	v_add_f32_e32 v114, v75, v66
	v_cvt_pk_bf16_f32 v140, v70, v71
	v_cvt_pk_bf16_f32 v141, v72, v73
	ds_read_b64_tr_b16 v[66:67], v203 offset:25600
	ds_read_b64_tr_b16 v[68:69], v203 offset:26112
	s_waitcnt lgkmcnt(11)
	v_mfma_f32_32x32x16_bf16 v[98:113], v[166:169], v[134:137], v[98:113]
	v_add_f32_e32 v70, v76, v114
	v_add_f32_e32 v70, v77, v70
	v_add_f32_e32 v70, v78, v70
	v_add_f32_e32 v114, v79, v70
	v_cvt_pk_bf16_f32 v130, v74, v75
	v_cvt_pk_bf16_f32 v131, v76, v77
	ds_read_b64_tr_b16 v[70:71], v203 offset:29696
	ds_read_b64_tr_b16 v[72:73], v203 offset:30208
	s_waitcnt lgkmcnt(12)
	v_mfma_f32_32x32x16_bf16 v[82:97], v[162:165], v[134:137], v[82:97]
	v_add_f32_e32 v74, v80, v114
	v_add_f32_e32 v74, v81, v74
	v_add_f32_e32 v74, v50, v74
	v_add_f32_e32 v114, v51, v74
	v_cvt_pk_bf16_f32 v132, v78, v79
	v_cvt_pk_bf16_f32 v133, v80, v81
	ds_read_b64_tr_b16 v[74:75], v203 offset:26624
	ds_read_b64_tr_b16 v[76:77], v203 offset:27136
	s_waitcnt lgkmcnt(13)
	v_mfma_f32_32x32x16_bf16 v[98:113], v[158:161], v[126:129], v[98:113]
	v_add_f32_e32 v78, v52, v114
	v_add_f32_e32 v78, v53, v78
	v_add_f32_e32 v78, v54, v78
	v_add_f32_e32 v78, v55, v78
	v_cvt_pk_bf16_f32 v122, v50, v51
	v_cvt_pk_bf16_f32 v123, v52, v53
	ds_read_b64_tr_b16 v[50:51], v203 offset:30720
	ds_read_b64_tr_b16 v[52:53], v203 offset:31232
	s_waitcnt lgkmcnt(14)
	v_mfma_f32_32x32x16_bf16 v[82:97], v[154:157], v[126:129], v[82:97]
	v_add_f32_e32 v78, v56, v78
	v_add_f32_e32 v78, v57, v78
	v_add_f32_e32 v78, v58, v78
	v_add_f32_e32 v78, v59, v78
	v_cvt_pk_bf16_f32 v124, v54, v55
	v_cvt_pk_bf16_f32 v125, v56, v57
	ds_read_b64_tr_b16 v[54:55], v203 offset:27648
	ds_read_b64_tr_b16 v[56:57], v203 offset:28160
	s_waitcnt lgkmcnt(14)
	v_mfma_f32_32x32x16_bf16 v[98:113], v[150:153], v[118:121], v[98:113]
	v_add_f32_e32 v78, v60, v78
	v_add_f32_e32 v78, v61, v78
	v_add_f32_e32 v78, v62, v78
	v_add_f32_e32 v78, v63, v78
	v_cvt_pk_bf16_f32 v114, v58, v59
	v_cvt_pk_bf16_f32 v115, v60, v61
	ds_read_b64_tr_b16 v[58:59], v203 offset:31744
	ds_read_b64_tr_b16 v[60:61], v203 offset:32256
	v_mfma_f32_32x32x16_bf16 v[82:97], v[146:149], v[118:121], v[82:97]
	v_add_f32_e32 v78, v64, v78
	v_add_f32_e32 v78, v65, v78
	v_cvt_pk_bf16_f32 v116, v62, v63
	v_cvt_pk_bf16_f32 v117, v64, v65
	s_waitcnt lgkmcnt(14)
	v_mfma_f32_32x32x16_bf16 v[18:33], v[138:141], v[178:181], v[18:33]
	s_add_i32 s98, s46, 0x2000
	s_mov_b32 s5, m0
	s_mov_b32 m0, s98
	s_nop 0
	global_load_lds_dwordx4 v188, s[100:101]
	s_mov_b32 m0, s5
	s_add_i32 s98, s47, 0x4000
	s_mov_b32 s5, m0
	s_mov_b32 m0, s98
	s_nop 0
	global_load_lds_dwordx4 v186, s[100:101]
	s_mov_b32 m0, s5
	v_add_f32_e32 v190, v205, v78
.Lf3_0_486:
	v_exp_f32_e32 v98, v98
	v_exp_f32_e32 v99, v99
	v_exp_f32_e32 v100, v100
	v_exp_f32_e32 v101, v101
	ds_read_b128 v[62:65], v202 offset:16384
	ds_read_b128 v[178:181], v202 offset:18432
	s_waitcnt lgkmcnt(14)
	v_mfma_f32_32x32x16_bf16 v[2:17], v[138:141], v[174:177], v[2:17]
	v_exp_f32_e32 v102, v102
	v_exp_f32_e32 v103, v103
	v_exp_f32_e32 v104, v104
	v_exp_f32_e32 v105, v105
	ds_read_b128 v[174:177], v202 offset:16896
	ds_read_b128 v[170:173], v202 offset:18944
	s_waitcnt lgkmcnt(14)
	v_mfma_f32_32x32x16_bf16 v[18:33], v[130:133], v[66:69], v[18:33]
	v_exp_f32_e32 v106, v106
	v_exp_f32_e32 v107, v107
	v_exp_f32_e32 v108, v108
	v_exp_f32_e32 v109, v109
	ds_read_b128 v[166:169], v202 offset:20480
	ds_read_b128 v[162:165], v202 offset:20992
	s_waitcnt lgkmcnt(14)
	v_mfma_f32_32x32x16_bf16 v[2:17], v[130:133], v[70:73], v[2:17]
	v_exp_f32_e32 v110, v110
	v_exp_f32_e32 v111, v111
	v_exp_f32_e32 v112, v112
	v_exp_f32_e32 v113, v113
	ds_read_b128 v[158:161], v202 offset:22528
	ds_read_b128 v[154:157], v202 offset:23040
	s_waitcnt lgkmcnt(14)
	v_mfma_f32_32x32x16_bf16 v[18:33], v[122:125], v[74:77], v[18:33]
	v_exp_f32_e32 v82, v82
	v_exp_f32_e32 v83, v83
	v_exp_f32_e32 v84, v84
	v_exp_f32_e32 v85, v85
	s_waitcnt lgkmcnt(12)
	v_mfma_f32_32x32x16_bf16 v[2:17], v[122:125], v[50:53], v[2:17]
	v_exp_f32_e32 v86, v86
	v_exp_f32_e32 v87, v87
	v_exp_f32_e32 v88, v88
	v_exp_f32_e32 v89, v89
	s_waitcnt lgkmcnt(10)
	v_mfma_f32_32x32x16_bf16 v[18:33], v[114:117], v[54:57], v[18:33]
	v_exp_f32_e32 v90, v90
	v_exp_f32_e32 v91, v91
	v_exp_f32_e32 v92, v92
	v_exp_f32_e32 v93, v93
	s_waitcnt vmcnt(2) lgkmcnt(0)
	s_barrier
	s_waitcnt lgkmcnt(8)
	v_mfma_f32_32x32x16_bf16 v[2:17], v[114:117], v[58:61], v[2:17]
	v_exp_f32_e32 v94, v94
	v_exp_f32_e32 v95, v95
	v_exp_f32_e32 v96, v96
	v_exp_f32_e32 v97, v97
.Lf3_0_488:
	s_waitcnt lgkmcnt(9)
	v_mfma_f32_32x32x16_bf16 v[66:81], v[62:65], v[142:145], v[34:49]
	ds_read_b64_tr_b16 v[150:151], v203 offset:32768
	ds_read_b64_tr_b16 v[152:153], v203 offset:33280
	v_add_f32_e32 v50, v98, v99
	v_add_f32_e32 v50, v100, v50
	v_add_f32_e32 v50, v101, v50
	v_add_f32_e32 v50, v102, v50
	v_add_f32_e32 v50, v103, v50
	v_cvt_pk_bf16_f32 v138, v98, v99
	v_cvt_pk_bf16_f32 v139, v100, v101
	ds_read_b64_tr_b16 v[146:147], v203 offset:36864
	ds_read_b64_tr_b16 v[148:149], v203 offset:37376
	v_add_f32_e32 v50, v104, v50
	v_add_f32_e32 v50, v105, v50
	v_add_f32_e32 v50, v106, v50
	v_add_f32_e32 v114, v107, v50
	s_waitcnt lgkmcnt(10)
	v_mfma_f32_32x32x16_bf16 v[50:65], v[174:177], v[142:145], v[34:49]
	v_cvt_pk_bf16_f32 v140, v102, v103
	v_cvt_pk_bf16_f32 v141, v104, v105
	ds_read_b64_tr_b16 v[98:99], v203 offset:33792
	ds_read_b64_tr_b16 v[100:101], v203 offset:34304
	s_waitcnt lgkmcnt(11)
	v_mfma_f32_32x32x16_bf16 v[66:81], v[178:181], v[134:137], v[66:81]
	v_add_f32_e32 v102, v108, v114
	v_add_f32_e32 v102, v109, v102
	v_add_f32_e32 v102, v110, v102
	v_add_f32_e32 v114, v111, v102
	v_cvt_pk_bf16_f32 v130, v106, v107
	v_cvt_pk_bf16_f32 v131, v108, v109
	ds_read_b64_tr_b16 v[102:103], v203 offset:37888
	ds_read_b64_tr_b16 v[104:105], v203 offset:38400
	s_waitcnt lgkmcnt(12)
	v_mfma_f32_32x32x16_bf16 v[50:65], v[170:173], v[134:137], v[50:65]
	v_add_f32_e32 v106, v112, v114
	v_add_f32_e32 v106, v113, v106
	v_add_f32_e32 v106, v82, v106
	v_add_f32_e32 v114, v83, v106
	v_cvt_pk_bf16_f32 v132, v110, v111
	v_cvt_pk_bf16_f32 v133, v112, v113
	ds_read_b64_tr_b16 v[106:107], v203 offset:34816
	ds_read_b64_tr_b16 v[108:109], v203 offset:35328
	s_waitcnt lgkmcnt(13)
	v_mfma_f32_32x32x16_bf16 v[66:81], v[166:169], v[126:129], v[66:81]
	v_add_f32_e32 v110, v84, v114
	v_add_f32_e32 v110, v85, v110
	v_add_f32_e32 v110, v86, v110
	v_add_f32_e32 v110, v87, v110
	v_cvt_pk_bf16_f32 v122, v82, v83
	v_cvt_pk_bf16_f32 v123, v84, v85
	ds_read_b64_tr_b16 v[82:83], v203 offset:38912
	ds_read_b64_tr_b16 v[84:85], v203 offset:39424
	s_waitcnt lgkmcnt(14)
	v_mfma_f32_32x32x16_bf16 v[50:65], v[162:165], v[126:129], v[50:65]
	v_add_f32_e32 v110, v88, v110
	v_add_f32_e32 v110, v89, v110
	v_add_f32_e32 v110, v90, v110
	v_add_f32_e32 v110, v91, v110
	v_cvt_pk_bf16_f32 v124, v86, v87
	v_cvt_pk_bf16_f32 v125, v88, v89
	ds_read_b64_tr_b16 v[86:87], v203 offset:35840
	ds_read_b64_tr_b16 v[88:89], v203 offset:36352
	s_waitcnt lgkmcnt(14)
	v_mfma_f32_32x32x16_bf16 v[66:81], v[158:161], v[118:121], v[66:81]
	v_add_f32_e32 v110, v92, v110
	v_add_f32_e32 v110, v93, v110
	v_add_f32_e32 v110, v94, v110
	v_add_f32_e32 v110, v95, v110
	v_cvt_pk_bf16_f32 v114, v90, v91
	v_cvt_pk_bf16_f32 v115, v92, v93
	ds_read_b64_tr_b16 v[90:91], v203 offset:39936
	ds_read_b64_tr_b16 v[92:93], v203 offset:40448
	v_mfma_f32_32x32x16_bf16 v[50:65], v[154:157], v[118:121], v[50:65]
	v_add_f32_e32 v110, v96, v110
	v_add_f32_e32 v110, v97, v110
	v_cvt_pk_bf16_f32 v116, v94, v95
	v_cvt_pk_bf16_f32 v117, v96, v97
	s_waitcnt lgkmcnt(14)
	v_mfma_f32_32x32x16_bf16 v[18:33], v[138:141], v[150:153], v[18:33]
	s_add_i32 s98, s46, 0x4000
	s_mov_b32 s5, m0
	s_mov_b32 m0, s98
	s_nop 0
	global_load_lds_dwordx4 v189, s[100:101]
	s_mov_b32 m0, s5
	s_add_i32 s98, s47, 0x0
	s_mov_b32 s5, m0
	s_mov_b32 m0, s98
	s_nop 0
	global_load_lds_dwordx4 v187, s[100:101]
	s_mov_b32 m0, s5
	v_add_f32_e32 v205, v190, v110
.Lf3_0_489:
	v_exp_f32_e32 v66, v66
	v_exp_f32_e32 v67, v67
	v_exp_f32_e32 v68, v68
	v_exp_f32_e32 v69, v69
	ds_read_b128 v[174:177], v202 offset:0
	ds_read_b128 v[170:173], v202 offset:512
	s_waitcnt lgkmcnt(14)
	v_mfma_f32_32x32x16_bf16 v[2:17], v[138:141], v[146:149], v[2:17]
	v_exp_f32_e32 v70, v70
	v_exp_f32_e32 v71, v71
	v_exp_f32_e32 v72, v72
	v_exp_f32_e32 v73, v73
	ds_read_b128 v[166:169], v202 offset:2048
	ds_read_b128 v[162:165], v202 offset:2560
	s_waitcnt lgkmcnt(14)
	v_mfma_f32_32x32x16_bf16 v[18:33], v[130:133], v[98:101], v[18:33]
	v_exp_f32_e32 v74, v74
	v_exp_f32_e32 v75, v75
	v_exp_f32_e32 v76, v76
	v_exp_f32_e32 v77, v77
	ds_read_b128 v[158:161], v202 offset:4096
	ds_read_b128 v[154:157], v202 offset:4608
	s_waitcnt lgkmcnt(14)
	v_mfma_f32_32x32x16_bf16 v[2:17], v[130:133], v[102:105], v[2:17]
	v_exp_f32_e32 v78, v78
	v_exp_f32_e32 v79, v79
	v_exp_f32_e32 v80, v80
	v_exp_f32_e32 v81, v81
	ds_read_b128 v[150:153], v202 offset:6144
	ds_read_b128 v[146:149], v202 offset:6656
	s_waitcnt lgkmcnt(14)
	v_mfma_f32_32x32x16_bf16 v[18:33], v[122:125], v[106:109], v[18:33]
	v_exp_f32_e32 v50, v50
	v_exp_f32_e32 v51, v51
	v_exp_f32_e32 v52, v52
	v_exp_f32_e32 v53, v53
	s_waitcnt lgkmcnt(12)
	v_mfma_f32_32x32x16_bf16 v[2:17], v[122:125], v[82:85], v[2:17]
	v_exp_f32_e32 v54, v54
	v_exp_f32_e32 v55, v55
	v_exp_f32_e32 v56, v56
	v_exp_f32_e32 v57, v57
	s_waitcnt lgkmcnt(10)
	v_mfma_f32_32x32x16_bf16 v[18:33], v[114:117], v[86:89], v[18:33]
	v_exp_f32_e32 v58, v58
	v_exp_f32_e32 v59, v59
	v_exp_f32_e32 v60, v60
	v_exp_f32_e32 v61, v61
	s_waitcnt vmcnt(2) lgkmcnt(0)
	s_barrier
	s_waitcnt lgkmcnt(8)
	v_mfma_f32_32x32x16_bf16 v[2:17], v[114:117], v[90:93], v[2:17]
	v_exp_f32_e32 v62, v62
	v_exp_f32_e32 v63, v63
	v_exp_f32_e32 v64, v64
	v_exp_f32_e32 v65, v65

.Lf3_1_485:
	s_waitcnt lgkmcnt(9)
	v_mfma_f32_32x32x16_bf16 v[98:113], v[174:177], v[142:145], v[34:49]
	ds_read_b64_tr_b16 v[178:179], v203 offset:40960
	ds_read_b64_tr_b16 v[180:181], v203 offset:41472
	v_add_f32_e32 v82, v66, v67
	v_add_f32_e32 v82, v68, v82
	v_add_f32_e32 v82, v69, v82
	v_add_f32_e32 v82, v70, v82
	v_add_f32_e32 v82, v71, v82
	v_cvt_pk_bf16_f32 v138, v66, v67
	v_cvt_pk_bf16_f32 v139, v68, v69
	ds_read_b64_tr_b16 v[174:175], v203 offset:45056
	ds_read_b64_tr_b16 v[176:177], v203 offset:45568
	v_add_f32_e32 v66, v72, v82
	s_waitcnt lgkmcnt(10)
	v_mfma_f32_32x32x16_bf16 v[82:97], v[170:173], v[142:145], v[34:49]
	v_add_f32_e32 v66, v73, v66
	v_add_f32_e32 v66, v74, v66
	v_add_f32_e32 v114, v75, v66
	v_cvt_pk_bf16_f32 v140, v70, v71
	v_cvt_pk_bf16_f32 v141, v72, v73
	ds_read_b64_tr_b16 v[66:67], v203 offset:41984
	ds_read_b64_tr_b16 v[68:69], v203 offset:42496
	s_waitcnt lgkmcnt(11)
	v_mfma_f32_32x32x16_bf16 v[98:113], v[166:169], v[134:137], v[98:113]
	v_add_f32_e32 v70, v76, v114
	v_add_f32_e32 v70, v77, v70
	v_add_f32_e32 v70, v78, v70
	v_add_f32_e32 v114, v79, v70
	v_cvt_pk_bf16_f32 v130, v74, v75
	v_cvt_pk_bf16_f32 v131, v76, v77
	ds_read_b64_tr_b16 v[70:71], v203 offset:46080
	ds_read_b64_tr_b16 v[72:73], v203 offset:46592
	s_waitcnt lgkmcnt(12)
	v_mfma_f32_32x32x16_bf16 v[82:97], v[162:165], v[134:137], v[82:97]
	v_add_f32_e32 v74, v80, v114
	v_add_f32_e32 v74, v81, v74
	v_add_f32_e32 v74, v50, v74
	v_add_f32_e32 v114, v51, v74
	v_cvt_pk_bf16_f32 v132, v78, v79
	v_cvt_pk_bf16_f32 v133, v80, v81
	ds_read_b64_tr_b16 v[74:75], v203 offset:43008
	ds_read_b64_tr_b16 v[76:77], v203 offset:43520
	s_waitcnt lgkmcnt(13)
	v_mfma_f32_32x32x16_bf16 v[98:113], v[158:161], v[126:129], v[98:113]
	v_add_f32_e32 v78, v52, v114
	v_add_f32_e32 v78, v53, v78
	v_add_f32_e32 v78, v54, v78
	v_add_f32_e32 v78, v55, v78
	v_cvt_pk_bf16_f32 v122, v50, v51
	v_cvt_pk_bf16_f32 v123, v52, v53
	ds_read_b64_tr_b16 v[50:51], v203 offset:47104
	ds_read_b64_tr_b16 v[52:53], v203 offset:47616
	s_waitcnt lgkmcnt(14)
	v_mfma_f32_32x32x16_bf16 v[82:97], v[154:157], v[126:129], v[82:97]
	v_add_f32_e32 v78, v56, v78
	v_add_f32_e32 v78, v57, v78
	v_add_f32_e32 v78, v58, v78
	v_add_f32_e32 v78, v59, v78
	v_cvt_pk_bf16_f32 v124, v54, v55
	v_cvt_pk_bf16_f32 v125, v56, v57
	ds_read_b64_tr_b16 v[54:55], v203 offset:44032
	ds_read_b64_tr_b16 v[56:57], v203 offset:44544
	s_waitcnt lgkmcnt(14)
	v_mfma_f32_32x32x16_bf16 v[98:113], v[150:153], v[118:121], v[98:113]
	v_add_f32_e32 v78, v60, v78
	v_add_f32_e32 v78, v61, v78
	v_add_f32_e32 v78, v62, v78
	v_add_f32_e32 v78, v63, v78
	v_cvt_pk_bf16_f32 v114, v58, v59
	v_cvt_pk_bf16_f32 v115, v60, v61
	ds_read_b64_tr_b16 v[58:59], v203 offset:48128
	ds_read_b64_tr_b16 v[60:61], v203 offset:48640
	v_mfma_f32_32x32x16_bf16 v[82:97], v[146:149], v[118:121], v[82:97]
	v_add_f32_e32 v78, v64, v78
	v_add_f32_e32 v78, v65, v78
	v_cvt_pk_bf16_f32 v116, v62, v63
	v_cvt_pk_bf16_f32 v117, v64, v65
	s_waitcnt lgkmcnt(14)
	v_mfma_f32_32x32x16_bf16 v[18:33], v[138:141], v[178:181], v[18:33]
	s_add_i32 s98, s46, 0x0
	s_mov_b32 s5, m0
	s_mov_b32 m0, s98
	s_nop 0
	global_load_lds_dwordx4 v188, s[100:101]
	s_mov_b32 m0, s5
	s_add_i32 s98, s47, 0x2000
	s_mov_b32 s5, m0
	s_mov_b32 m0, s98
	s_nop 0
	global_load_lds_dwordx4 v186, s[100:101]
	s_mov_b32 m0, s5
	v_add_f32_e32 v190, v205, v78
.Lf3_1_486:
	v_exp_f32_e32 v98, v98
	v_exp_f32_e32 v99, v99
	v_exp_f32_e32 v100, v100
	v_exp_f32_e32 v101, v101
	ds_read_b128 v[62:65], v202 offset:8192
	ds_read_b128 v[178:181], v202 offset:10240
	s_waitcnt lgkmcnt(14)
	v_mfma_f32_32x32x16_bf16 v[2:17], v[138:141], v[174:177], v[2:17]
	v_exp_f32_e32 v102, v102
	v_exp_f32_e32 v103, v103
	v_exp_f32_e32 v104, v104
	v_exp_f32_e32 v105, v105
	ds_read_b128 v[174:177], v202 offset:8704
	ds_read_b128 v[170:173], v202 offset:10752
	s_waitcnt lgkmcnt(14)
	v_mfma_f32_32x32x16_bf16 v[18:33], v[130:133], v[66:69], v[18:33]
	v_exp_f32_e32 v106, v106
	v_exp_f32_e32 v107, v107
	v_exp_f32_e32 v108, v108
	v_exp_f32_e32 v109, v109
	ds_read_b128 v[166:169], v202 offset:12288
	ds_read_b128 v[162:165], v202 offset:12800
	s_waitcnt lgkmcnt(14)
	v_mfma_f32_32x32x16_bf16 v[2:17], v[130:133], v[70:73], v[2:17]
	v_exp_f32_e32 v110, v110
	v_exp_f32_e32 v111, v111
	v_exp_f32_e32 v112, v112
	v_exp_f32_e32 v113, v113
	ds_read_b128 v[158:161], v202 offset:14336
	ds_read_b128 v[154:157], v202 offset:14848
	s_waitcnt lgkmcnt(14)
	v_mfma_f32_32x32x16_bf16 v[18:33], v[122:125], v[74:77], v[18:33]
	v_exp_f32_e32 v82, v82
	v_exp_f32_e32 v83, v83
	v_exp_f32_e32 v84, v84
	v_exp_f32_e32 v85, v85
	s_waitcnt lgkmcnt(12)
	v_mfma_f32_32x32x16_bf16 v[2:17], v[122:125], v[50:53], v[2:17]
	v_exp_f32_e32 v86, v86
	v_exp_f32_e32 v87, v87
	v_exp_f32_e32 v88, v88
	v_exp_f32_e32 v89, v89
	s_waitcnt lgkmcnt(10)
	v_mfma_f32_32x32x16_bf16 v[18:33], v[114:117], v[54:57], v[18:33]
	v_exp_f32_e32 v90, v90
	v_exp_f32_e32 v91, v91
	v_exp_f32_e32 v92, v92
	v_exp_f32_e32 v93, v93
	s_waitcnt vmcnt(2) lgkmcnt(0)
	s_barrier
	s_waitcnt lgkmcnt(8)
	v_mfma_f32_32x32x16_bf16 v[2:17], v[114:117], v[58:61], v[2:17]
	v_exp_f32_e32 v94, v94
	v_exp_f32_e32 v95, v95
	v_exp_f32_e32 v96, v96
	v_exp_f32_e32 v97, v97
.Lf3_1_488:
	s_waitcnt lgkmcnt(9)
	v_mfma_f32_32x32x16_bf16 v[66:81], v[62:65], v[142:145], v[34:49]
	ds_read_b64_tr_b16 v[150:151], v203 offset:24576
	ds_read_b64_tr_b16 v[152:153], v203 offset:25088
	v_add_f32_e32 v50, v98, v99
	v_add_f32_e32 v50, v100, v50
	v_add_f32_e32 v50, v101, v50
	v_add_f32_e32 v50, v102, v50
	v_add_f32_e32 v50, v103, v50
	v_cvt_pk_bf16_f32 v138, v98, v99
	v_cvt_pk_bf16_f32 v139, v100, v101
	ds_read_b64_tr_b16 v[146:147], v203 offset:28672
	ds_read_b64_tr_b16 v[148:149], v203 offset:29184
	v_add_f32_e32 v50, v104, v50
	v_add_f32_e32 v50, v105, v50
	v_add_f32_e32 v50, v106, v50
	v_add_f32_e32 v114, v107, v50
	s_waitcnt lgkmcnt(10)
	v_mfma_f32_32x32x16_bf16 v[50:65], v[174:177], v[142:145], v[34:49]
	v_cvt_pk_bf16_f32 v140, v102, v103
	v_cvt_pk_bf16_f32 v141, v104, v105
	ds_read_b64_tr_b16 v[98:99], v203 offset:25600
	ds_read_b64_tr_b16 v[100:101], v203 offset:26112
	s_waitcnt lgkmcnt(11)
	v_mfma_f32_32x32x16_bf16 v[66:81], v[178:181], v[134:137], v[66:81]
	v_add_f32_e32 v102, v108, v114
	v_add_f32_e32 v102, v109, v102
	v_add_f32_e32 v102, v110, v102
	v_add_f32_e32 v114, v111, v102
	v_cvt_pk_bf16_f32 v130, v106, v107
	v_cvt_pk_bf16_f32 v131, v108, v109
	ds_read_b64_tr_b16 v[102:103], v203 offset:29696
	ds_read_b64_tr_b16 v[104:105], v203 offset:30208
	s_waitcnt lgkmcnt(12)
	v_mfma_f32_32x32x16_bf16 v[50:65], v[170:173], v[134:137], v[50:65]
	v_add_f32_e32 v106, v112, v114
	v_add_f32_e32 v106, v113, v106
	v_add_f32_e32 v106, v82, v106
	v_add_f32_e32 v114, v83, v106
	v_cvt_pk_bf16_f32 v132, v110, v111
	v_cvt_pk_bf16_f32 v133, v112, v113
	ds_read_b64_tr_b16 v[106:107], v203 offset:26624
	ds_read_b64_tr_b16 v[108:109], v203 offset:27136
	s_waitcnt lgkmcnt(13)
	v_mfma_f32_32x32x16_bf16 v[66:81], v[166:169], v[126:129], v[66:81]
	v_add_f32_e32 v110, v84, v114
	v_add_f32_e32 v110, v85, v110
	v_add_f32_e32 v110, v86, v110
	v_add_f32_e32 v110, v87, v110
	v_cvt_pk_bf16_f32 v122, v82, v83
	v_cvt_pk_bf16_f32 v123, v84, v85
	ds_read_b64_tr_b16 v[82:83], v203 offset:30720
	ds_read_b64_tr_b16 v[84:85], v203 offset:31232
	s_waitcnt lgkmcnt(14)
	v_mfma_f32_32x32x16_bf16 v[50:65], v[162:165], v[126:129], v[50:65]
	v_add_f32_e32 v110, v88, v110
	v_add_f32_e32 v110, v89, v110
	v_add_f32_e32 v110, v90, v110
	v_add_f32_e32 v110, v91, v110
	v_cvt_pk_bf16_f32 v124, v86, v87
	v_cvt_pk_bf16_f32 v125, v88, v89
	ds_read_b64_tr_b16 v[86:87], v203 offset:27648
	ds_read_b64_tr_b16 v[88:89], v203 offset:28160
	s_waitcnt lgkmcnt(14)
	v_mfma_f32_32x32x16_bf16 v[66:81], v[158:161], v[118:121], v[66:81]
	v_add_f32_e32 v110, v92, v110
	v_add_f32_e32 v110, v93, v110
	v_add_f32_e32 v110, v94, v110
	v_add_f32_e32 v110, v95, v110
	v_cvt_pk_bf16_f32 v114, v90, v91
	v_cvt_pk_bf16_f32 v115, v92, v93
	ds_read_b64_tr_b16 v[90:91], v203 offset:31744
	ds_read_b64_tr_b16 v[92:93], v203 offset:32256
	v_mfma_f32_32x32x16_bf16 v[50:65], v[154:157], v[118:121], v[50:65]
	v_add_f32_e32 v110, v96, v110
	v_add_f32_e32 v110, v97, v110
	v_cvt_pk_bf16_f32 v116, v94, v95
	v_cvt_pk_bf16_f32 v117, v96, v97
	s_waitcnt lgkmcnt(14)
	v_mfma_f32_32x32x16_bf16 v[18:33], v[138:141], v[150:153], v[18:33]
	s_add_i32 s98, s46, 0x2000
	s_mov_b32 s5, m0
	s_mov_b32 m0, s98
	s_nop 0
	global_load_lds_dwordx4 v189, s[100:101]
	s_mov_b32 m0, s5
	s_add_i32 s98, s47, 0x4000
	s_mov_b32 s5, m0
	s_mov_b32 m0, s98
	s_nop 0
	global_load_lds_dwordx4 v187, s[100:101]
	s_mov_b32 m0, s5
	v_add_f32_e32 v205, v190, v110
.Lf3_1_489:
	v_exp_f32_e32 v66, v66
	v_exp_f32_e32 v67, v67
	v_exp_f32_e32 v68, v68
	v_exp_f32_e32 v69, v69
	ds_read_b128 v[174:177], v202 offset:16384
	ds_read_b128 v[170:173], v202 offset:16896
	s_waitcnt lgkmcnt(14)
	v_mfma_f32_32x32x16_bf16 v[2:17], v[138:141], v[146:149], v[2:17]
	v_exp_f32_e32 v70, v70
	v_exp_f32_e32 v71, v71
	v_exp_f32_e32 v72, v72
	v_exp_f32_e32 v73, v73
	ds_read_b128 v[166:169], v202 offset:18432
	ds_read_b128 v[162:165], v202 offset:18944
	s_waitcnt lgkmcnt(14)
	v_mfma_f32_32x32x16_bf16 v[18:33], v[130:133], v[98:101], v[18:33]
	v_exp_f32_e32 v74, v74
	v_exp_f32_e32 v75, v75
	v_exp_f32_e32 v76, v76
	v_exp_f32_e32 v77, v77
	ds_read_b128 v[158:161], v202 offset:20480
	ds_read_b128 v[154:157], v202 offset:20992
	s_waitcnt lgkmcnt(14)
	v_mfma_f32_32x32x16_bf16 v[2:17], v[130:133], v[102:105], v[2:17]
	v_exp_f32_e32 v78, v78
	v_exp_f32_e32 v79, v79
	v_exp_f32_e32 v80, v80
	v_exp_f32_e32 v81, v81
	ds_read_b128 v[150:153], v202 offset:22528
	ds_read_b128 v[146:149], v202 offset:23040
	s_waitcnt lgkmcnt(14)
	v_mfma_f32_32x32x16_bf16 v[18:33], v[122:125], v[106:109], v[18:33]
	v_exp_f32_e32 v50, v50
	v_exp_f32_e32 v51, v51
	v_exp_f32_e32 v52, v52
	v_exp_f32_e32 v53, v53
	s_waitcnt lgkmcnt(12)
	v_mfma_f32_32x32x16_bf16 v[2:17], v[122:125], v[82:85], v[2:17]
	v_exp_f32_e32 v54, v54
	v_exp_f32_e32 v55, v55
	v_exp_f32_e32 v56, v56
	v_exp_f32_e32 v57, v57
	s_waitcnt lgkmcnt(10)
	v_mfma_f32_32x32x16_bf16 v[18:33], v[114:117], v[86:89], v[18:33]
	v_exp_f32_e32 v58, v58
	v_exp_f32_e32 v59, v59
	v_exp_f32_e32 v60, v60
	v_exp_f32_e32 v61, v61
	s_waitcnt vmcnt(2) lgkmcnt(0)
	s_barrier
	s_waitcnt lgkmcnt(8)
	v_mfma_f32_32x32x16_bf16 v[2:17], v[114:117], v[90:93], v[2:17]
	v_exp_f32_e32 v62, v62
	v_exp_f32_e32 v63, v63
	v_exp_f32_e32 v64, v64
	v_exp_f32_e32 v65, v65

.Lf3_2_485:
	s_waitcnt lgkmcnt(9)
	v_mfma_f32_32x32x16_bf16 v[98:113], v[174:177], v[142:145], v[34:49]
	ds_read_b64_tr_b16 v[178:179], v203 offset:32768
	ds_read_b64_tr_b16 v[180:181], v203 offset:33280
	v_add_f32_e32 v82, v66, v67
	v_add_f32_e32 v82, v68, v82
	v_add_f32_e32 v82, v69, v82
	v_add_f32_e32 v82, v70, v82
	v_add_f32_e32 v82, v71, v82
	v_cvt_pk_bf16_f32 v138, v66, v67
	v_cvt_pk_bf16_f32 v139, v68, v69
	ds_read_b64_tr_b16 v[174:175], v203 offset:36864
	ds_read_b64_tr_b16 v[176:177], v203 offset:37376
	v_add_f32_e32 v66, v72, v82
	s_waitcnt lgkmcnt(10)
	v_mfma_f32_32x32x16_bf16 v[82:97], v[170:173], v[142:145], v[34:49]
	v_add_f32_e32 v66, v73, v66
	v_add_f32_e32 v66, v74, v66
	v_add_f32_e32 v114, v75, v66
	v_cvt_pk_bf16_f32 v140, v70, v71
	v_cvt_pk_bf16_f32 v141, v72, v73
	ds_read_b64_tr_b16 v[66:67], v203 offset:33792
	ds_read_b64_tr_b16 v[68:69], v203 offset:34304
	s_waitcnt lgkmcnt(11)
	v_mfma_f32_32x32x16_bf16 v[98:113], v[166:169], v[134:137], v[98:113]
	v_add_f32_e32 v70, v76, v114
	v_add_f32_e32 v70, v77, v70
	v_add_f32_e32 v70, v78, v70
	v_add_f32_e32 v114, v79, v70
	v_cvt_pk_bf16_f32 v130, v74, v75
	v_cvt_pk_bf16_f32 v131, v76, v77
	ds_read_b64_tr_b16 v[70:71], v203 offset:37888
	ds_read_b64_tr_b16 v[72:73], v203 offset:38400
	s_waitcnt lgkmcnt(12)
	v_mfma_f32_32x32x16_bf16 v[82:97], v[162:165], v[134:137], v[82:97]
	v_add_f32_e32 v74, v80, v114
	v_add_f32_e32 v74, v81, v74
	v_add_f32_e32 v74, v50, v74
	v_add_f32_e32 v114, v51, v74
	v_cvt_pk_bf16_f32 v132, v78, v79
	v_cvt_pk_bf16_f32 v133, v80, v81
	ds_read_b64_tr_b16 v[74:75], v203 offset:34816
	ds_read_b64_tr_b16 v[76:77], v203 offset:35328
	s_waitcnt lgkmcnt(13)
	v_mfma_f32_32x32x16_bf16 v[98:113], v[158:161], v[126:129], v[98:113]
	v_add_f32_e32 v78, v52, v114
	v_add_f32_e32 v78, v53, v78
	v_add_f32_e32 v78, v54, v78
	v_add_f32_e32 v78, v55, v78
	v_cvt_pk_bf16_f32 v122, v50, v51
	v_cvt_pk_bf16_f32 v123, v52, v53
	ds_read_b64_tr_b16 v[50:51], v203 offset:38912
	ds_read_b64_tr_b16 v[52:53], v203 offset:39424
	s_waitcnt lgkmcnt(14)
	v_mfma_f32_32x32x16_bf16 v[82:97], v[154:157], v[126:129], v[82:97]
	v_add_f32_e32 v78, v56, v78
	v_add_f32_e32 v78, v57, v78
	v_add_f32_e32 v78, v58, v78
	v_add_f32_e32 v78, v59, v78
	v_cvt_pk_bf16_f32 v124, v54, v55
	v_cvt_pk_bf16_f32 v125, v56, v57
	ds_read_b64_tr_b16 v[54:55], v203 offset:35840
	ds_read_b64_tr_b16 v[56:57], v203 offset:36352
	s_waitcnt lgkmcnt(14)
	v_mfma_f32_32x32x16_bf16 v[98:113], v[150:153], v[118:121], v[98:113]
	v_add_f32_e32 v78, v60, v78
	v_add_f32_e32 v78, v61, v78
	v_add_f32_e32 v78, v62, v78
	v_add_f32_e32 v78, v63, v78
	v_cvt_pk_bf16_f32 v114, v58, v59
	v_cvt_pk_bf16_f32 v115, v60, v61
	ds_read_b64_tr_b16 v[58:59], v203 offset:39936
	ds_read_b64_tr_b16 v[60:61], v203 offset:40448
	v_mfma_f32_32x32x16_bf16 v[82:97], v[146:149], v[118:121], v[82:97]
	v_add_f32_e32 v78, v64, v78
	v_add_f32_e32 v78, v65, v78
	v_cvt_pk_bf16_f32 v116, v62, v63
	v_cvt_pk_bf16_f32 v117, v64, v65
	s_waitcnt lgkmcnt(14)
	v_mfma_f32_32x32x16_bf16 v[18:33], v[138:141], v[178:181], v[18:33]
	s_add_i32 s98, s46, 0x4000
	s_mov_b32 s5, m0
	s_mov_b32 m0, s98
	s_nop 0
	global_load_lds_dwordx4 v188, s[100:101]
	s_mov_b32 m0, s5
	s_add_i32 s98, s47, 0x0
	s_mov_b32 s5, m0
	s_mov_b32 m0, s98
	s_nop 0
	global_load_lds_dwordx4 v186, s[100:101]
	s_mov_b32 m0, s5
	v_add_f32_e32 v190, v205, v78
.Lf3_2_486:
	v_exp_f32_e32 v98, v98
	v_exp_f32_e32 v99, v99
	v_exp_f32_e32 v100, v100
	v_exp_f32_e32 v101, v101
	ds_read_b128 v[62:65], v202 offset:0
	ds_read_b128 v[178:181], v202 offset:2048
	s_waitcnt lgkmcnt(14)
	v_mfma_f32_32x32x16_bf16 v[2:17], v[138:141], v[174:177], v[2:17]
	v_exp_f32_e32 v102, v102
	v_exp_f32_e32 v103, v103
	v_exp_f32_e32 v104, v104
	v_exp_f32_e32 v105, v105
	ds_read_b128 v[174:177], v202 offset:512
	ds_read_b128 v[170:173], v202 offset:2560
	s_waitcnt lgkmcnt(14)
	v_mfma_f32_32x32x16_bf16 v[18:33], v[130:133], v[66:69], v[18:33]
	v_exp_f32_e32 v106, v106
	v_exp_f32_e32 v107, v107
	v_exp_f32_e32 v108, v108
	v_exp_f32_e32 v109, v109
	ds_read_b128 v[166:169], v202 offset:4096
	ds_read_b128 v[162:165], v202 offset:4608
	s_waitcnt lgkmcnt(14)
	v_mfma_f32_32x32x16_bf16 v[2:17], v[130:133], v[70:73], v[2:17]
	v_exp_f32_e32 v110, v110
	v_exp_f32_e32 v111, v111
	v_exp_f32_e32 v112, v112
	v_exp_f32_e32 v113, v113
	ds_read_b128 v[158:161], v202 offset:6144
	ds_read_b128 v[154:157], v202 offset:6656
	s_waitcnt lgkmcnt(14)
	v_mfma_f32_32x32x16_bf16 v[18:33], v[122:125], v[74:77], v[18:33]
	v_exp_f32_e32 v82, v82
	v_exp_f32_e32 v83, v83
	v_exp_f32_e32 v84, v84
	v_exp_f32_e32 v85, v85
	s_waitcnt lgkmcnt(12)
	v_mfma_f32_32x32x16_bf16 v[2:17], v[122:125], v[50:53], v[2:17]
	v_exp_f32_e32 v86, v86
	v_exp_f32_e32 v87, v87
	v_exp_f32_e32 v88, v88
	v_exp_f32_e32 v89, v89
	s_waitcnt lgkmcnt(10)
	v_mfma_f32_32x32x16_bf16 v[18:33], v[114:117], v[54:57], v[18:33]
	v_exp_f32_e32 v90, v90
	v_exp_f32_e32 v91, v91
	v_exp_f32_e32 v92, v92
	v_exp_f32_e32 v93, v93
	s_waitcnt vmcnt(2) lgkmcnt(0)
	s_barrier
	s_waitcnt lgkmcnt(8)
	v_mfma_f32_32x32x16_bf16 v[2:17], v[114:117], v[58:61], v[2:17]
	v_exp_f32_e32 v94, v94
	v_exp_f32_e32 v95, v95
	v_exp_f32_e32 v96, v96
	v_exp_f32_e32 v97, v97
.Lf3_2_488:
	s_waitcnt lgkmcnt(9)
	v_mfma_f32_32x32x16_bf16 v[66:81], v[62:65], v[142:145], v[34:49]
	ds_read_b64_tr_b16 v[150:151], v203 offset:40960
	ds_read_b64_tr_b16 v[152:153], v203 offset:41472
	v_add_f32_e32 v50, v98, v99
	v_add_f32_e32 v50, v100, v50
	v_add_f32_e32 v50, v101, v50
	v_add_f32_e32 v50, v102, v50
	v_add_f32_e32 v50, v103, v50
	v_cvt_pk_bf16_f32 v138, v98, v99
	v_cvt_pk_bf16_f32 v139, v100, v101
	ds_read_b64_tr_b16 v[146:147], v203 offset:45056
	ds_read_b64_tr_b16 v[148:149], v203 offset:45568
	v_add_f32_e32 v50, v104, v50
	v_add_f32_e32 v50, v105, v50
	v_add_f32_e32 v50, v106, v50
	v_add_f32_e32 v114, v107, v50
	s_waitcnt lgkmcnt(10)
	v_mfma_f32_32x32x16_bf16 v[50:65], v[174:177], v[142:145], v[34:49]
	v_cvt_pk_bf16_f32 v140, v102, v103
	v_cvt_pk_bf16_f32 v141, v104, v105
	ds_read_b64_tr_b16 v[98:99], v203 offset:41984
	ds_read_b64_tr_b16 v[100:101], v203 offset:42496
	s_waitcnt lgkmcnt(11)
	v_mfma_f32_32x32x16_bf16 v[66:81], v[178:181], v[134:137], v[66:81]
	v_add_f32_e32 v102, v108, v114
	v_add_f32_e32 v102, v109, v102
	v_add_f32_e32 v102, v110, v102
	v_add_f32_e32 v114, v111, v102
	v_cvt_pk_bf16_f32 v130, v106, v107
	v_cvt_pk_bf16_f32 v131, v108, v109
	ds_read_b64_tr_b16 v[102:103], v203 offset:46080
	ds_read_b64_tr_b16 v[104:105], v203 offset:46592
	s_waitcnt lgkmcnt(12)
	v_mfma_f32_32x32x16_bf16 v[50:65], v[170:173], v[134:137], v[50:65]
	v_add_f32_e32 v106, v112, v114
	v_add_f32_e32 v106, v113, v106
	v_add_f32_e32 v106, v82, v106
	v_add_f32_e32 v114, v83, v106
	v_cvt_pk_bf16_f32 v132, v110, v111
	v_cvt_pk_bf16_f32 v133, v112, v113
	ds_read_b64_tr_b16 v[106:107], v203 offset:43008
	ds_read_b64_tr_b16 v[108:109], v203 offset:43520
	s_waitcnt lgkmcnt(13)
	v_mfma_f32_32x32x16_bf16 v[66:81], v[166:169], v[126:129], v[66:81]
	v_add_f32_e32 v110, v84, v114
	v_add_f32_e32 v110, v85, v110
	v_add_f32_e32 v110, v86, v110
	v_add_f32_e32 v110, v87, v110
	v_cvt_pk_bf16_f32 v122, v82, v83
	v_cvt_pk_bf16_f32 v123, v84, v85
	ds_read_b64_tr_b16 v[82:83], v203 offset:47104
	ds_read_b64_tr_b16 v[84:85], v203 offset:47616
	s_waitcnt lgkmcnt(14)
	v_mfma_f32_32x32x16_bf16 v[50:65], v[162:165], v[126:129], v[50:65]
	v_add_f32_e32 v110, v88, v110
	v_add_f32_e32 v110, v89, v110
	v_add_f32_e32 v110, v90, v110
	v_add_f32_e32 v110, v91, v110
	v_cvt_pk_bf16_f32 v124, v86, v87
	v_cvt_pk_bf16_f32 v125, v88, v89
	ds_read_b64_tr_b16 v[86:87], v203 offset:44032
	ds_read_b64_tr_b16 v[88:89], v203 offset:44544
	s_waitcnt lgkmcnt(14)
	v_mfma_f32_32x32x16_bf16 v[66:81], v[158:161], v[118:121], v[66:81]
	v_add_f32_e32 v110, v92, v110
	v_add_f32_e32 v110, v93, v110
	v_add_f32_e32 v110, v94, v110
	v_add_f32_e32 v110, v95, v110
	v_cvt_pk_bf16_f32 v114, v90, v91
	v_cvt_pk_bf16_f32 v115, v92, v93
	ds_read_b64_tr_b16 v[90:91], v203 offset:48128
	ds_read_b64_tr_b16 v[92:93], v203 offset:48640
	v_mfma_f32_32x32x16_bf16 v[50:65], v[154:157], v[118:121], v[50:65]
	v_add_f32_e32 v110, v96, v110
	v_add_f32_e32 v110, v97, v110
	v_cvt_pk_bf16_f32 v116, v94, v95
	v_cvt_pk_bf16_f32 v117, v96, v97
	s_waitcnt lgkmcnt(14)
	v_mfma_f32_32x32x16_bf16 v[18:33], v[138:141], v[150:153], v[18:33]
	s_add_i32 s98, s46, 0x0
	s_mov_b32 s5, m0
	s_mov_b32 m0, s98
	s_nop 0
	global_load_lds_dwordx4 v189, s[100:101]
	s_mov_b32 m0, s5
	s_add_i32 s98, s47, 0x2000
	s_mov_b32 s5, m0
	s_mov_b32 m0, s98
	s_nop 0
	global_load_lds_dwordx4 v187, s[100:101]
	s_mov_b32 m0, s5
	v_add_f32_e32 v205, v190, v110
.Lf3_2_489:
	v_exp_f32_e32 v66, v66
	v_exp_f32_e32 v67, v67
	v_exp_f32_e32 v68, v68
	v_exp_f32_e32 v69, v69
	ds_read_b128 v[174:177], v202 offset:8192
	ds_read_b128 v[170:173], v202 offset:8704
	s_waitcnt lgkmcnt(14)
	v_mfma_f32_32x32x16_bf16 v[2:17], v[138:141], v[146:149], v[2:17]
	v_exp_f32_e32 v70, v70
	v_exp_f32_e32 v71, v71
	v_exp_f32_e32 v72, v72
	v_exp_f32_e32 v73, v73
	ds_read_b128 v[166:169], v202 offset:10240
	ds_read_b128 v[162:165], v202 offset:10752
	s_waitcnt lgkmcnt(14)
	v_mfma_f32_32x32x16_bf16 v[18:33], v[130:133], v[98:101], v[18:33]
	v_exp_f32_e32 v74, v74
	v_exp_f32_e32 v75, v75
	v_exp_f32_e32 v76, v76
	v_exp_f32_e32 v77, v77
	ds_read_b128 v[158:161], v202 offset:12288
	ds_read_b128 v[154:157], v202 offset:12800
	s_waitcnt lgkmcnt(14)
	v_mfma_f32_32x32x16_bf16 v[2:17], v[130:133], v[102:105], v[2:17]
	v_exp_f32_e32 v78, v78
	v_exp_f32_e32 v79, v79
	v_exp_f32_e32 v80, v80
	v_exp_f32_e32 v81, v81
	ds_read_b128 v[150:153], v202 offset:14336
	ds_read_b128 v[146:149], v202 offset:14848
	s_waitcnt lgkmcnt(14)
	v_mfma_f32_32x32x16_bf16 v[18:33], v[122:125], v[106:109], v[18:33]
	v_exp_f32_e32 v50, v50
	v_exp_f32_e32 v51, v51
	v_exp_f32_e32 v52, v52
	v_exp_f32_e32 v53, v53
	s_waitcnt lgkmcnt(12)
	v_mfma_f32_32x32x16_bf16 v[2:17], v[122:125], v[82:85], v[2:17]
	v_exp_f32_e32 v54, v54
	v_exp_f32_e32 v55, v55
	v_exp_f32_e32 v56, v56
	v_exp_f32_e32 v57, v57
	s_waitcnt lgkmcnt(10)
	v_mfma_f32_32x32x16_bf16 v[18:33], v[114:117], v[86:89], v[18:33]
	v_exp_f32_e32 v58, v58
	v_exp_f32_e32 v59, v59
	v_exp_f32_e32 v60, v60
	v_exp_f32_e32 v61, v61
	s_waitcnt vmcnt(2) lgkmcnt(0)
	s_barrier
	s_waitcnt lgkmcnt(8)
	v_mfma_f32_32x32x16_bf16 v[2:17], v[114:117], v[90:93], v[2:17]
	v_exp_f32_e32 v62, v62
	v_exp_f32_e32 v63, v63
	v_exp_f32_e32 v64, v64
	v_exp_f32_e32 v65, v65
